# chunk GEMM prologue: row-statistics loads stay in flight, rsqrt+table write deferred to the last prologue barrier
# speedup vs baseline: 1.0035x; 1.0035x over previous
.LBB0_917:
	s_mov_b32 s100, 0
	s_min_i32 s6, s14, 2
	s_lshl_b32 s53, s6, 1
	s_sub_i32 s61, 6, s53
	s_mov_b32 s28, 0
	s_and_b64 vcc, exec, s[4:5]
	s_cbranch_vccnz .LBB0_935
	s_lshl_b32 s22, s18, 8
	v_cmp_gt_i32_e32 vcc, s22, v2
	s_and_saveexec_b64 s[6:7], vcc
	s_cbranch_execz .LBB0_934
	v_and_b32_e32 v0, 15, v2
	s_waitcnt lgkmcnt(0)
	s_add_u32 s10, s8, 0x1000000
	v_subrev_co_u32_e32 v1, vcc, 4, v0
	v_cmp_gt_u32_e64 s[40:41], 12, v0
	s_addc_u32 s11, s9, 0
	s_lshl_b32 s14, -1, s61
	v_cndmask_b32_e64 v1, v0, v1, s[40:41]
	v_add_u32_e32 v4, 4, v0
	v_cmp_gt_u32_e64 s[40:41], 8, v0
	s_not_b32 s23, s14
	v_readlane_b32 s14, v253, 59
	v_cndmask_b32_e64 v1, v1, v4, s[40:41]
	v_and_b32_e32 v3, 0xff, v2
	v_cndmask_b32_e32 v4, v1, v0, vcc
	v_lshl_add_u32 v5, v2, 2, s14
	s_mov_b64 s[14:15], 0
	s_cmp_eq_u32 s18, 6
	s_cbranch_scc1 .Lrt_fast
	s_cmp_eq_u32 s18, 4
	s_cbranch_scc0 .LBB0_921
.Lrt_fast:
	v_mov_b32_e32 v212, v5
	s_mov_b32 s100, 2
	v_ashrrev_i32_e32 v6, 8, v2
	v_mov_b64_e32 v[0:1], s[2:3]
	v_mad_i64_i32 v[0:1], s[18:19], v6, s52, v[0:1]
	v_cmp_gt_i64_e64 s[20:21], s[44:45], v[0:1]
	v_cmp_le_i64_e32 vcc, s[44:45], v[0:1]
	v_mov_b32_e32 v7, 64
	v_mov_b32_e32 v6, 0
	v_mov_b32_e32 v8, s30
	s_and_saveexec_b64 s[18:19], vcc
	v_subrev_co_u32_e32 v0, vcc, s44, v0
	s_andn2_b64 s[20:21], s[20:21], exec
	s_nop 0
	v_subbrev_co_u32_e32 v1, vcc, 0, v1, vcc
	v_cmp_gt_i64_e32 vcc, s[46:47], v[0:1]
	s_and_b64 s[24:25], vcc, exec
	v_mov_b32_e32 v8, 64
	v_mov_b32_e32 v6, 1
	v_mov_b32_e32 v7, s59
	s_or_b64 s[20:21], s[20:21], s[24:25]
	s_or_b64 exec, exec, s[18:19]
	s_and_saveexec_b64 s[18:19], s[20:21]
	s_cbranch_execz .Lrt0_929
	v_mul_i32_i24_e32 v1, v7, v8
	v_lshrrev_b32_e32 v11, 3, v1
	v_and_b32_e32 v12, 7, v1
	v_ashrrev_i32_e32 v1, 31, v0
	v_lshrrev_b32_e32 v1, 29, v1
	v_add_u32_e32 v1, v0, v1
	v_and_b32_e32 v9, -8, v1
	v_sub_u32_e32 v9, v0, v9
	v_cmp_ge_i32_e32 vcc, v9, v12
	v_add_u32_e32 v10, 1, v11
	s_and_saveexec_b64 s[20:21], vcc
	s_xor_b64 s[20:21], exec, s[20:21]
	v_sub_u32_e32 v0, v9, v12
	v_mul_lo_u32 v0, v0, v11
	v_mad_u32_u24 v0, v10, v12, v0
	s_andn2_saveexec_b64 s[20:21], s[20:21]
	v_mul_lo_u32 v0, v9, v10
	s_or_b64 exec, exec, s[20:21]
	v_ashrrev_i32_e32 v1, 3, v1
	v_add_u32_e32 v0, v0, v1
	v_lshlrev_b32_e32 v1, 3, v8
	v_sub_u32_e32 v10, 0, v1
	v_max_i32_e32 v10, v1, v10
	v_cvt_f32_u32_e32 v11, v10
	v_sub_u32_e32 v12, 0, v10
	v_sub_u32_e32 v9, 0, v0
	v_max_i32_e32 v9, v0, v9
	v_rcp_iflag_f32_e32 v11, v11
	v_xor_b32_e32 v8, v0, v1
	v_ashrrev_i32_e32 v8, 31, v8
	v_mov_b32_e32 v188, v6
	v_mul_f32_e32 v11, 0x4f7ffffe, v11
	v_cvt_u32_f32_e32 v11, v11
	v_mul_lo_u32 v12, v12, v11
	v_mul_hi_u32 v12, v11, v12
	v_add_u32_e32 v11, v11, v12
	v_mul_hi_u32 v11, v9, v11
	v_mul_lo_u32 v12, v11, v10
	v_sub_u32_e32 v9, v9, v12
	v_cmp_ge_u32_e32 vcc, v9, v10
	v_add_u32_e32 v12, 1, v11
	s_nop 0
	v_cndmask_b32_e32 v11, v11, v12, vcc
	v_sub_u32_e32 v12, v9, v10
	v_cndmask_b32_e32 v9, v9, v12, vcc
	v_cmp_ge_u32_e32 vcc, v9, v10
	v_add_u32_e32 v9, 1, v11
	s_nop 0
	v_cndmask_b32_e32 v9, v11, v9, vcc
	v_xor_b32_e32 v9, v9, v8
	v_sub_u32_e32 v8, v9, v8
	v_lshlrev_b32_e32 v9, 3, v8
	v_sub_u32_e32 v7, v7, v9
	v_min_i32_e32 v7, 8, v7
	v_sub_u32_e32 v10, 0, v7
	v_max_i32_e32 v10, v7, v10
	v_cvt_f32_u32_e32 v11, v10
	v_mul_lo_u32 v1, v8, v1
	v_sub_u32_e32 v12, 0, v10
	v_sub_u32_e32 v0, v0, v1
	v_rcp_iflag_f32_e32 v11, v11
	v_sub_u32_e32 v8, 0, v0
	v_max_i32_e32 v8, v0, v8
	v_xor_b32_e32 v1, v0, v7
	v_mul_f32_e32 v11, 0x4f7ffffe, v11
	v_cvt_u32_f32_e32 v11, v11
	v_ashrrev_i32_e32 v1, 31, v1
	v_mul_lo_u32 v12, v12, v11
	v_mul_hi_u32 v12, v11, v12
	v_add_u32_e32 v11, v11, v12
	v_mul_hi_u32 v11, v8, v11
	v_mul_lo_u32 v12, v11, v10
	v_sub_u32_e32 v8, v8, v12
	v_cmp_ge_u32_e32 vcc, v8, v10
	v_add_u32_e32 v12, 1, v11
	s_nop 0
	v_cndmask_b32_e32 v11, v11, v12, vcc
	v_sub_u32_e32 v12, v8, v10
	v_cndmask_b32_e32 v8, v8, v12, vcc
	v_cmp_ge_u32_e32 vcc, v8, v10
	v_add_u32_e32 v8, 1, v11
	s_nop 0
	v_cndmask_b32_e32 v8, v11, v8, vcc
	v_xor_b32_e32 v8, v8, v1
	v_sub_u32_e32 v189, v8, v1
	v_mul_lo_u32 v1, v189, v7
	v_sub_u32_e32 v0, v0, v1
	v_add_u32_e32 v190, v0, v9

.Lrt2_920:
	s_or_b64 exec, exec, s[18:19]
	v_ashrrev_i32_e32 v1, 31, v0
	v_lshl_add_u64 v[0:1], v[0:1], 4, s[10:11]
	global_load_dwordx4 v[208:211], v[0:1], off
	v_add_u32_e32 v2, 0x200, v2
	s_mov_b32 s100, 3
.Lrt_issued:
	s_or_b64 exec, exec, s[6:7]
	v_readlane_b32 s28, v253, 59
	s_branch .LBB0_935
	s_branch .LBB0_921

.LBB0_957:
	s_lshl_b32 s22, s22, 5
	s_and_b32 s69, s22, 0x60
	s_lshl_b32 s68, s31, 6
	s_lshl_b32 s23, s31, 13
	s_lshl_b32 s22, s69, 7
	v_and_b32_e32 v13, 48, v12
	v_lshlrev_b32_e32 v14, 6, v12
	s_movk_i32 s24, 0x3c0
	v_lshlrev_b32_e32 v12, 2, v12
	s_add_u32 s70, s8, 0x4000000
	v_and_or_b32 v13, v14, s24, v13
	v_and_b32_e32 v12, 32, v12
	s_addc_u32 s71, s9, 0
	v_bitop3_b32 v194, s22, v13, v12 bitop3:0xf6
	s_add_u32 s22, s8, 0x1000000
	v_bitop3_b32 v14, v13, s23, v12 bitop3:0xde
	s_addc_u32 s23, s9, 0
	s_add_u32 s24, s8, 0xc000000
	s_addc_u32 s25, s9, 0
	s_add_i32 m0, s62, 0x18000
	v_lshl_add_u64 v[0:1], v[0:1], 0, s[16:17]
	s_waitcnt vmcnt(2)
	s_barrier
	global_load_lds_dwordx4 v[0:1], off
	v_lshl_add_u64 v[0:1], v[2:3], 0, s[16:17]
	s_add_i32 m0, s62, 0x1a000
	s_add_i32 s72, s62, 0x8000
	global_load_lds_dwordx4 v[0:1], off
	v_lshl_add_u64 v[0:1], v[8:9], 0, s[16:17]
	s_mov_b32 m0, s72
	s_add_i32 s73, s62, 0xa000
	global_load_lds_dwordx4 v[0:1], off
	v_lshl_add_u64 v[0:1], v[10:11], 0, s[16:17]
	s_mov_b32 m0, s73
	s_mov_b32 s83, 0
	global_load_lds_dwordx4 v[0:1], off
	s_add_i32 m0, s62, 0x1c000
	v_lshl_add_u64 v[0:1], v[4:5], 0, s[16:17]
	global_load_lds_dwordx4 v[0:1], off
	v_lshl_add_u64 v[0:1], v[6:7], 0, s[16:17]
	s_add_i32 m0, s62, 0x1e000
	s_cmpk_lt_u32 s29, 0x100
	global_load_lds_dwordx4 v[0:1], off
	s_cselect_b64 s[26:27], -1, 0
	s_lshl_b32 s29, s69, 2
	s_add_i32 s74, s28, s29
	s_lshl_b32 s29, s31, 8
	s_lshl_b32 s31, -1, s61
	s_add_i32 s75, s28, s29
	s_lshl_b64 s[28:29], s[56:57], 8
	s_not_b32 s76, s31
	s_waitcnt vmcnt(6)
	s_and_b64 s[12:13], s[12:13], exec
	s_cselect_b32 s77, 25, 24
	s_lshl_b32 s12, -1, s60
	s_not_b32 s78, s12
	s_sub_i32 s79, 14, s53
	s_lshl_b32 s80, s30, 3
	v_add_u32_e32 v195, 0, v14
	s_cmp_eq_u32 s100, 0
	s_cbranch_scc1 .Lrt_done
	v_add_f32_e32 v213, v201, v200
	v_add_f32_e32 v214, v202, v203
	v_add_f32_e32 v213, v213, v214
	v_fmamk_f32 v213, v213, 0x3a800000, v172
	v_cmp_gt_f32_e32 vcc, s33, v213
	v_mul_f32_e32 v214, 0x4b800000, v213
	s_nop 0
	v_cndmask_b32_e32 v213, v213, v214, vcc
	v_rsq_f32_e32 v213, v213
	s_nop 0
	v_mul_f32_e32 v214, 0x45800000, v213
	v_cndmask_b32_e32 v213, v213, v214, vcc
	ds_write_b32 v212, v213
	v_add_u32_e32 v212, 0x800, v212
	v_add_f32_e32 v213, v205, v204
	v_add_f32_e32 v214, v206, v207
	v_add_f32_e32 v213, v213, v214
	v_fmamk_f32 v213, v213, 0x3a800000, v172
	v_cmp_gt_f32_e32 vcc, s33, v213
	v_mul_f32_e32 v214, 0x4b800000, v213
	s_nop 0
	v_cndmask_b32_e32 v213, v213, v214, vcc
	v_rsq_f32_e32 v213, v213
	s_nop 0
	v_mul_f32_e32 v214, 0x45800000, v213
	v_cndmask_b32_e32 v213, v213, v214, vcc
	ds_write_b32 v212, v213
	v_add_u32_e32 v212, 0x800, v212
	s_cmp_eq_u32 s100, 2
	s_cbranch_scc1 .Lrt_fin
	v_add_f32_e32 v213, v209, v208
	v_add_f32_e32 v214, v210, v211
	v_add_f32_e32 v213, v213, v214
	v_fmamk_f32 v213, v213, 0x3a800000, v172
	v_cmp_gt_f32_e32 vcc, s33, v213
	v_mul_f32_e32 v214, 0x4b800000, v213
	s_nop 0
	v_cndmask_b32_e32 v213, v213, v214, vcc
	v_rsq_f32_e32 v213, v213
	s_nop 0
	v_mul_f32_e32 v214, 0x45800000, v213
	v_cndmask_b32_e32 v213, v213, v214, vcc
	ds_write_b32 v212, v213
	v_add_u32_e32 v212, 0x800, v212

.Lrt_done:
	s_barrier
	s_branch .LBB0_960

	.amdhsa_kernel _Z8yoco_fwd6Params
		.amdhsa_group_segment_fixed_size 0
		.amdhsa_private_segment_fixed_size 0
		.amdhsa_kernarg_size 384
		.amdhsa_user_sgpr_count 2
		.amdhsa_user_sgpr_dispatch_ptr 0
		.amdhsa_user_sgpr_queue_ptr 0
		.amdhsa_user_sgpr_kernarg_segment_ptr 1
		.amdhsa_user_sgpr_dispatch_id 0
		.amdhsa_user_sgpr_kernarg_preload_length 0
		.amdhsa_user_sgpr_kernarg_preload_offset 0
		.amdhsa_user_sgpr_private_segment_size 0
		.amdhsa_uses_dynamic_stack 0
		.amdhsa_enable_private_segment 0
		.amdhsa_system_sgpr_workgroup_id_x 1
		.amdhsa_system_sgpr_workgroup_id_y 0
		.amdhsa_system_sgpr_workgroup_id_z 0
		.amdhsa_system_sgpr_workgroup_info 0
		.amdhsa_system_vgpr_workitem_id 2
		.amdhsa_next_free_vgpr 256
		.amdhsa_next_free_sgpr 102
		.amdhsa_accum_offset 256
		.amdhsa_reserve_vcc 1
		.amdhsa_float_round_mode_32 0
		.amdhsa_float_round_mode_16_64 0
		.amdhsa_float_denorm_mode_32 3
		.amdhsa_float_denorm_mode_16_64 3
		.amdhsa_dx10_clamp 1
		.amdhsa_ieee_mode 1
		.amdhsa_fp16_overflow 0
		.amdhsa_tg_split 0
		.amdhsa_exception_fp_ieee_invalid_op 0
		.amdhsa_exception_fp_denorm_src 0
		.amdhsa_exception_fp_ieee_div_zero 0
		.amdhsa_exception_fp_ieee_overflow 0
		.amdhsa_exception_fp_ieee_underflow 0
		.amdhsa_exception_fp_ieee_inexact 0
		.amdhsa_exception_int_div_zero 0
	.end_amdhsa_kernel
